# grid seams: the acquire invalidate is issued and awaited by wave 1 right after the arrival barrier, off the polling wave's path
# baseline (speedup 1.0000x reference)
.LBB0_88:
	v_readlane_b32 s9, v246, 5
	s_lshl_b32 s9, s9, 8
	v_readlane_b32 s10, v246, 3
	v_readlane_b32 s11, v246, 4
	s_add_u32 s10, s10, s9
	s_addc_u32 s11, s11, 0
	v_mov_b32_e32 v1, 0x1000
	v_mov_b32_e32 v3, 1
	v_sub_u32_e32 v4, 0, v2
	global_atomic_add v3, v1, v3, s[10:11] offset:1024 sc0
	v_cvt_f32_u32_e32 v1, v2
	v_rcp_iflag_f32_e32 v1, v1
	s_nop 0
	v_mul_f32_e32 v1, 0x4f7ffffe, v1
	v_cvt_u32_f32_e32 v1, v1
	v_mul_lo_u32 v4, v4, v1
	v_mul_hi_u32 v4, v1, v4
	v_add_u32_e32 v1, v1, v4
	s_waitcnt vmcnt(0)
	v_mul_hi_u32 v1, v3, v1
	v_mul_lo_u32 v4, v1, v2
	v_sub_u32_e32 v4, v3, v4
	v_add_u32_e32 v5, 1, v1
	v_cmp_ge_u32_e32 vcc, v4, v2
	v_add_u32_e32 v3, 1, v3
	s_nop 0
	v_cndmask_b32_e32 v1, v1, v5, vcc
	v_sub_u32_e32 v5, v4, v2
	v_cndmask_b32_e32 v4, v4, v5, vcc
	v_add_u32_e32 v5, 1, v1
	v_cmp_ge_u32_e32 vcc, v4, v2
	s_nop 1
	v_cndmask_b32_e32 v1, v1, v5, vcc
	v_mul_lo_u32 v4, v2, v1
	v_add_u32_e32 v2, v4, v2
	v_cmp_ne_u32_e32 vcc, v3, v2
	s_cbranch_vccnz .Lxg_nl_1
	buffer_wbl2 sc1
	s_waitcnt vmcnt(0)
	v_readlane_b32 s98, v246, 3
	v_readlane_b32 s99, v246, 4
	v_mov_b32_e32 v14, 1
	v_mov_b32_e32 v6, 0x2400
	v_mov_b32_e32 v7, 0x2500
	v_mov_b32_e32 v8, 0x2600
	v_mov_b32_e32 v9, 0x2700
	v_mov_b32_e32 v10, 0x2800
	v_mov_b32_e32 v11, 0x2900
	v_mov_b32_e32 v12, 0x2a00
	v_mov_b32_e32 v13, 0x2b00
	global_atomic_add v6, v14, s[98:99]
	global_atomic_add v7, v14, s[98:99]
	global_atomic_add v8, v14, s[98:99]
	global_atomic_add v9, v14, s[98:99]
	global_atomic_add v10, v14, s[98:99]
	global_atomic_add v11, v14, s[98:99]
	global_atomic_add v12, v14, s[98:99]
	global_atomic_add v13, v14, s[98:99]
	s_mov_b64 vcc, exec
.Lxg_nl_1:
	s_and_saveexec_b64 s[12:13], vcc
	s_xor_b64 s[12:13], exec, s[12:13]
	s_cbranch_execz .LBB0_102
	s_waitcnt lgkmcnt(0)
	v_mad_u32_u24 v5, v1, v0, v0
	v_mov_b32_e32 v0, 0x2000
	global_load_dword v0, v0, s[10:11] offset:1024 sc1
	s_add_u32 s18, s10, 0x2400
	s_addc_u32 s19, s11, 0
	s_waitcnt vmcnt(0)
	v_cmp_lt_u32_e32 vcc, v0, v5
	s_and_saveexec_b64 s[14:15], vcc
	s_cbranch_execz .LBB0_101
	s_add_u32 s16, s54, 0xd600200
	s_addc_u32 s17, s55, 0
	s_mov_b32 s9, 1
	s_mov_b64 s[20:21], 0
	v_mov_b32_e32 v0, 0
	s_branch .LBB0_92

.LBB0_120:
	s_or_b64 exec, exec, s[4:5]
	s_cmp_lg_u32 s94, 1
	s_cbranch_scc1 .Lw1inv_1
	buffer_inv sc1
	s_waitcnt vmcnt(0)
.Lw1inv_1:
	s_waitcnt lgkmcnt(0)
	s_barrier

.LBB0_150:
	v_readlane_b32 s3, v246, 5
	s_lshl_b32 s3, s3, 8
	v_readlane_b32 s8, v246, 3
	v_readlane_b32 s9, v246, 4
	s_add_u32 s8, s8, s3
	s_addc_u32 s9, s9, 0
	v_mov_b32_e32 v1, 0x1000
	v_mov_b32_e32 v3, 1
	v_sub_u32_e32 v4, 0, v2
	global_atomic_add v3, v1, v3, s[8:9] offset:1024 sc0
	v_cvt_f32_u32_e32 v1, v2
	v_rcp_iflag_f32_e32 v1, v1
	s_nop 0
	v_mul_f32_e32 v1, 0x4f7ffffe, v1
	v_cvt_u32_f32_e32 v1, v1
	v_mul_lo_u32 v4, v4, v1
	v_mul_hi_u32 v4, v1, v4
	v_add_u32_e32 v1, v1, v4
	s_waitcnt vmcnt(0)
	v_mul_hi_u32 v1, v3, v1
	v_mul_lo_u32 v4, v1, v2
	v_sub_u32_e32 v4, v3, v4
	v_add_u32_e32 v5, 1, v1
	v_cmp_ge_u32_e32 vcc, v4, v2
	v_add_u32_e32 v3, 1, v3
	s_nop 0
	v_cndmask_b32_e32 v1, v1, v5, vcc
	v_sub_u32_e32 v5, v4, v2
	v_cndmask_b32_e32 v4, v4, v5, vcc
	v_add_u32_e32 v5, 1, v1
	v_cmp_ge_u32_e32 vcc, v4, v2
	s_nop 1
	v_cndmask_b32_e32 v1, v1, v5, vcc
	v_mul_lo_u32 v4, v2, v1
	v_add_u32_e32 v2, v4, v2
	v_cmp_ne_u32_e32 vcc, v3, v2
	s_cbranch_vccnz .Lxg_nl_2
	buffer_wbl2 sc1
	s_waitcnt vmcnt(0)
	v_readlane_b32 s98, v246, 3
	v_readlane_b32 s99, v246, 4
	v_mov_b32_e32 v14, 1
	v_mov_b32_e32 v6, 0x2400
	v_mov_b32_e32 v7, 0x2500
	v_mov_b32_e32 v8, 0x2600
	v_mov_b32_e32 v9, 0x2700
	v_mov_b32_e32 v10, 0x2800
	v_mov_b32_e32 v11, 0x2900
	v_mov_b32_e32 v12, 0x2a00
	v_mov_b32_e32 v13, 0x2b00
	global_atomic_add v6, v14, s[98:99]
	global_atomic_add v7, v14, s[98:99]
	global_atomic_add v8, v14, s[98:99]
	global_atomic_add v9, v14, s[98:99]
	global_atomic_add v10, v14, s[98:99]
	global_atomic_add v11, v14, s[98:99]
	global_atomic_add v12, v14, s[98:99]
	global_atomic_add v13, v14, s[98:99]
	s_mov_b64 vcc, exec
.Lxg_nl_2:
	s_and_saveexec_b64 s[10:11], vcc
	s_xor_b64 s[10:11], exec, s[10:11]
	s_cbranch_execz .LBB0_164
	s_waitcnt lgkmcnt(0)
	v_mad_u32_u24 v5, v1, v0, v0
	v_mov_b32_e32 v0, 0x2000
	global_load_dword v0, v0, s[8:9] offset:1024 sc1
	s_add_u32 s16, s8, 0x2400
	s_addc_u32 s17, s9, 0
	s_waitcnt vmcnt(0)
	v_cmp_lt_u32_e32 vcc, v0, v5
	s_and_saveexec_b64 s[12:13], vcc
	s_cbranch_execz .LBB0_163
	s_add_u32 s14, s54, 0xd600200
	s_addc_u32 s15, s55, 0
	s_mov_b32 s3, 1
	s_mov_b64 s[18:19], 0
	v_mov_b32_e32 v0, 0
	s_branch .LBB0_154

.LBB0_182:
	s_or_b64 exec, exec, s[0:1]
	s_cmp_lg_u32 s94, 1
	s_cbranch_scc1 .Lw1inv_2
	buffer_inv sc1
	s_waitcnt vmcnt(0)

.LBB0_223:
	v_readlane_b32 s3, v246, 5
	s_lshl_b32 s3, s3, 8
	v_readlane_b32 s6, v246, 3
	v_readlane_b32 s7, v246, 4
	s_add_u32 s6, s6, s3
	s_addc_u32 s7, s7, 0
	v_mov_b32_e32 v1, 0x1000
	v_mov_b32_e32 v3, 1
	v_sub_u32_e32 v4, 0, v2
	global_atomic_add v3, v1, v3, s[6:7] offset:1024 sc0
	v_cvt_f32_u32_e32 v1, v2
	v_rcp_iflag_f32_e32 v1, v1
	s_nop 0
	v_mul_f32_e32 v1, 0x4f7ffffe, v1
	v_cvt_u32_f32_e32 v1, v1
	v_mul_lo_u32 v4, v4, v1
	v_mul_hi_u32 v4, v1, v4
	v_add_u32_e32 v1, v1, v4
	s_waitcnt vmcnt(0)
	v_mul_hi_u32 v1, v3, v1
	v_mul_lo_u32 v4, v1, v2
	v_sub_u32_e32 v4, v3, v4
	v_add_u32_e32 v5, 1, v1
	v_cmp_ge_u32_e32 vcc, v4, v2
	v_add_u32_e32 v3, 1, v3
	s_nop 0
	v_cndmask_b32_e32 v1, v1, v5, vcc
	v_sub_u32_e32 v5, v4, v2
	v_cndmask_b32_e32 v4, v4, v5, vcc
	v_add_u32_e32 v5, 1, v1
	v_cmp_ge_u32_e32 vcc, v4, v2
	s_nop 1
	v_cndmask_b32_e32 v1, v1, v5, vcc
	v_mul_lo_u32 v4, v2, v1
	v_add_u32_e32 v2, v4, v2
	v_cmp_ne_u32_e32 vcc, v3, v2
	s_cbranch_vccnz .Lxg_nl_3
	buffer_wbl2 sc1
	s_waitcnt vmcnt(0)
	v_readlane_b32 s98, v246, 3
	v_readlane_b32 s99, v246, 4
	v_mov_b32_e32 v14, 1
	v_mov_b32_e32 v6, 0x2400
	v_mov_b32_e32 v7, 0x2500
	v_mov_b32_e32 v8, 0x2600
	v_mov_b32_e32 v9, 0x2700
	v_mov_b32_e32 v10, 0x2800
	v_mov_b32_e32 v11, 0x2900
	v_mov_b32_e32 v12, 0x2a00
	v_mov_b32_e32 v13, 0x2b00
	global_atomic_add v6, v14, s[98:99]
	global_atomic_add v7, v14, s[98:99]
	global_atomic_add v8, v14, s[98:99]
	global_atomic_add v9, v14, s[98:99]
	global_atomic_add v10, v14, s[98:99]
	global_atomic_add v11, v14, s[98:99]
	global_atomic_add v12, v14, s[98:99]
	global_atomic_add v13, v14, s[98:99]
	s_mov_b64 vcc, exec
.Lxg_nl_3:
	s_and_saveexec_b64 s[8:9], vcc
	s_xor_b64 s[8:9], exec, s[8:9]
	s_cbranch_execz .LBB0_237
	s_waitcnt lgkmcnt(0)
	v_mad_u32_u24 v5, v1, v0, v0
	v_mov_b32_e32 v0, 0x2000
	global_load_dword v0, v0, s[6:7] offset:1024 sc1
	s_add_u32 s14, s6, 0x2400
	s_addc_u32 s15, s7, 0
	s_waitcnt vmcnt(0)
	v_cmp_lt_u32_e32 vcc, v0, v5
	s_and_saveexec_b64 s[10:11], vcc
	s_cbranch_execz .LBB0_236
	s_add_u32 s12, s54, 0xd600200
	s_addc_u32 s13, s55, 0
	s_mov_b32 s3, 1
	s_mov_b64 s[16:17], 0
	v_mov_b32_e32 v0, 0
	s_branch .LBB0_227

.Lxg_nl_7:
	s_and_saveexec_b64 s[8:9], vcc
	s_xor_b64 s[8:9], exec, s[8:9]
	s_cbranch_execz .LBB0_603
	s_waitcnt lgkmcnt(0)
	v_mad_u32_u24 v5, v1, v0, v0
	v_mov_b32_e32 v0, 0x2000
	global_load_dword v0, v0, s[6:7] offset:1024 sc1
	s_add_u32 s22, s6, 0x2400
	s_addc_u32 s23, s7, 0
	s_waitcnt vmcnt(0)
	v_cmp_lt_u32_e32 vcc, v0, v5
	s_and_saveexec_b64 s[10:11], vcc
	s_cbranch_execz .LBB0_602
	s_add_u32 s14, s54, 0xd600200
	s_addc_u32 s15, s55, 0
	s_mov_b32 s3, 1
	s_mov_b64 s[28:29], 0
	v_mov_b32_e32 v0, 0
	s_branch .LBB0_593

.Lxg_nl_8:
	s_and_saveexec_b64 s[8:9], vcc
	s_xor_b64 s[8:9], exec, s[8:9]
	s_cbranch_execz .LBB0_858
	s_waitcnt lgkmcnt(0)
	v_mad_u32_u24 v5, v1, v0, v0
	v_mov_b32_e32 v0, 0x2000
	global_load_dword v0, v0, s[6:7] offset:1024 sc1
	s_add_u32 s22, s6, 0x2400
	s_addc_u32 s23, s7, 0
	s_waitcnt vmcnt(0)
	v_cmp_lt_u32_e32 vcc, v0, v5
	s_and_saveexec_b64 s[10:11], vcc
	s_cbranch_execz .LBB0_857
	s_add_u32 s20, s54, 0xd600200
	s_addc_u32 s21, s55, 0
	s_mov_b32 s3, 1
	s_mov_b64 s[60:61], 0
	v_mov_b32_e32 v0, 0
	s_branch .LBB0_848
